# v31 V-side stack on top of the PV0-first diff M segment (V-fragment block prefetched at the end of the previous M)
# baseline (speedup 1.0000x reference)
; __device__ __forceinline__ float max3f(float a, float b, float c) { return __builtin_fmaxf(__builtin_fmaxf(a, b), c); }
; __device__ __forceinline__ void rowmax_adjust(f32x16& p0, f32x16& p1, float& m2, f32x16& negm, float& alpha, const bool first) {
;     constexpr float THR2 = THR * 1.4426950408889634f;
;     float pmax = max3f(p0[0], p0[1], p0[2]);
; #pragma unroll
;     for (int r = 3; r < 15; r += 2) pmax = max3f(pmax, p0[r], p0[r + 1]);
;     pmax = max3f(pmax, p0[15], p1[0]);
; #pragma unroll
;     for (int r = 1; r < 15; r += 2) pmax = max3f(pmax, p1[r], p1[r + 1]);
;     pmax = fmaxf(pmax, p1[15]);
;     { auto rr = __builtin_amdgcn_permlane32_swap(__float_as_uint(pmax), __float_as_uint(pmax), false, false);
;       pmax = fmaxf(__uint_as_float(rr[0]), __uint_as_float(rr[1])); }
;     if (!first && __builtin_expect(__all(pmax <= THR2), 1)) { alpha = 1.f; }
.Ld3_ae_nopv:
	s_waitcnt lgkmcnt(0)
	s_and_b32 s0, s51, 0xc000
	v_add_u32_e32 v240, s0, v217
	ds_read_b64_tr_b16 v[164:165], v240 offset:0
	ds_read_b64_tr_b16 v[166:167], v240 offset:0x800
	ds_read_b64_tr_b16 v[160:161], v240 offset:0x1000
	ds_read_b64_tr_b16 v[162:163], v240 offset:0x1800
	ds_read_b64_tr_b16 v[156:157], v240 offset:0x2000
	ds_read_b64_tr_b16 v[158:159], v240 offset:0x2800
	ds_read_b64_tr_b16 v[152:153], v240 offset:0x3000
	ds_read_b64_tr_b16 v[154:155], v240 offset:0x3800
	s_mov_b64 s[0:1], s[72:73]
	s_barrier
	v_max3_f32 v168, v96, v97, v98
	v_exp_f32_e32 v240, v96
	v_max3_f32 v169, v81, v82, v83
	v_exp_f32_e32 v241, v97
	v_max3_f32 v168, v168, v99, v100
	v_exp_f32_e32 v242, v98
	v_max3_f32 v169, v169, v84, v85
	v_exp_f32_e32 v243, v99
	v_max3_f32 v168, v168, v101, v102
	v_exp_f32_e32 v244, v100
	v_max3_f32 v169, v169, v86, v87
	v_exp_f32_e32 v245, v101
	v_max3_f32 v168, v168, v103, v104
	v_exp_f32_e32 v246, v102
	v_max3_f32 v169, v169, v88, v89
	v_exp_f32_e32 v247, v103
	v_max3_f32 v168, v168, v105, v106
	v_exp_f32_e32 v248, v104
	v_max3_f32 v169, v169, v90, v91
	v_exp_f32_e32 v249, v105
	v_max3_f32 v168, v168, v107, v108
	v_exp_f32_e32 v250, v106
	v_max3_f32 v169, v169, v92, v93
	v_exp_f32_e32 v251, v107
	v_max3_f32 v168, v168, v109, v110
	v_exp_f32_e32 v252, v108
	v_max3_f32 v169, v169, v94, v95
	v_exp_f32_e32 v253, v109
	v_max3_f32 v168, v168, v111, v80
	v_exp_f32_e32 v236, v110
	v_max_f32_e32 v168, v168, v169
	v_exp_f32_e32 v237, v111
	v_mov_b32_e32 v169, v168
	s_nop 1
	v_permlane32_swap_b32_e32 v168, v169
	v_max_f32_e32 v168, v168, v169
	v_cmp_ge_f32_e32 vcc, s83, v168
	v_mov_b32_e32 v184, 1.0
	s_cmp_lg_u64 s[0:1], 0
	s_cbranch_scc1 .Lvt0_first
	s_cmp_lg_u64 vcc, exec
	s_cbranch_scc1 .Lvt0_rare
	s_branch .Lsp_de0

; __device__ __forceinline__ float max3f(float a, float b, float c) { return __builtin_fmaxf(__builtin_fmaxf(a, b), c); }
; __device__ __forceinline__ void rowmax_adjust(f32x16& p0, f32x16& p1, float& m2, f32x16& negm, float& alpha, const bool first) {
;     constexpr float THR2 = THR * 1.4426950408889634f;
;     float pmax = max3f(p0[0], p0[1], p0[2]);
; #pragma unroll
;     for (int r = 3; r < 15; r += 2) pmax = max3f(pmax, p0[r], p0[r + 1]);
;     pmax = max3f(pmax, p0[15], p1[0]);
; #pragma unroll
;     for (int r = 1; r < 15; r += 2) pmax = max3f(pmax, p1[r], p1[r + 1]);
;     pmax = fmaxf(pmax, p1[15]);
;     { auto rr = __builtin_amdgcn_permlane32_swap(__float_as_uint(pmax), __float_as_uint(pmax), false, false);
;       pmax = fmaxf(__uint_as_float(rr[0]), __uint_as_float(rr[1])); }
;     if (!first && __builtin_expect(__all(pmax <= THR2), 1)) { alpha = 1.f; }
.LBB0_1164:
	s_min_u32 s0, s95, 0x7f
	s_lshl_b32 s0, s0, 16
	s_add_i32 s16, s0, 0x40000
	s_add_u32 s0, s58, s16
	s_addc_u32 s1, s59, 0
	global_load_dwordx4 v[132:135], v200, s[0:1]
	global_load_dwordx4 v[128:131], v202, s[0:1]
	v_lshl_add_u64 v[80:81], v[204:205], 0, s[16:17]
	global_load_dwordx4 v[136:139], v[80:81], off
	s_waitcnt lgkmcnt(0)
	s_barrier
	s_or_b32 s0, s95, 1
	s_and_b32 s1, s0, 0xff
	s_mulk_i32 s1, 0xab
	s_bfe_u32 s1, s1, 0x70009
	s_mul_i32 s1, s1, 3
	s_sub_i32 s0, s0, s1
	s_and_b32 s0, s0, 0xff
	s_mulk_i32 s0, 0x2400
	v_add_u32_e32 v84, s0, v218
	s_and_b32 s0, s51, 0x8000
	v_add_u32_e32 v187, s0, v217
	ds_read_b128 v[80:83], v84
	ds_read_b128 v[192:195], v84 offset:4608
	ds_read_b128 v[188:191], v84 offset:32
	ds_read_b128 v[196:199], v84 offset:4640
	ds_read_b128 v[220:223], v84 offset:64
	ds_read_b128 v[228:231], v84 offset:4672
	ds_read_b128 v[224:227], v84 offset:96
	ds_read_b128 v[232:235], v84 offset:4704
	v_mfma_f32_32x32x16_bf16 v[48:63], v[180:183], v[164:167], v[48:63]
	v_mfma_f32_32x32x16_bf16 v[48:63], v[176:179], v[160:163], v[48:63]
	v_mfma_f32_32x32x16_bf16 v[48:63], v[172:175], v[156:159], v[48:63]
	v_mfma_f32_32x32x16_bf16 v[48:63], v[168:171], v[152:155], v[48:63]
	s_waitcnt lgkmcnt(7)
	v_mfma_f32_32x32x16_bf16 v[96:111], v[80:83], v[112:115], v[64:79]
	s_waitcnt lgkmcnt(6)
	v_mfma_f32_32x32x16_bf16 v[80:95], v[192:195], v[112:115], v[64:79]
	s_waitcnt lgkmcnt(5)
	v_mfma_f32_32x32x16_bf16 v[96:111], v[188:191], v[116:119], v[96:111]
	s_waitcnt lgkmcnt(4)
	v_mfma_f32_32x32x16_bf16 v[80:95], v[196:199], v[116:119], v[80:95]
	s_waitcnt lgkmcnt(0)
	ds_read_b64_tr_b16 v[188:189], v187 offset:0x200
	ds_read_b64_tr_b16 v[190:191], v187 offset:0xa00
	ds_read_b64_tr_b16 v[192:193], v187 offset:0x1200
	ds_read_b64_tr_b16 v[194:195], v187 offset:0x1a00
	ds_read_b64_tr_b16 v[196:197], v187 offset:0x2200
	ds_read_b64_tr_b16 v[198:199], v187 offset:0x2a00
	ds_read_b64_tr_b16 v[236:237], v187 offset:0x3200
	ds_read_b64_tr_b16 v[238:239], v187 offset:0x3a00
	ds_read_b64_tr_b16 v[164:165], v187 offset:0x400
	ds_read_b64_tr_b16 v[166:167], v187 offset:0xc00
	ds_read_b64_tr_b16 v[160:161], v187 offset:0x1400
	ds_read_b64_tr_b16 v[162:163], v187 offset:0x1c00
	ds_read_b64_tr_b16 v[156:157], v187 offset:0x2400
	ds_read_b64_tr_b16 v[158:159], v187 offset:0x2c00
	ds_read_b64_tr_b16 v[152:153], v187 offset:0x3400
	ds_read_b64_tr_b16 v[154:155], v187 offset:0x3c00
	v_mfma_f32_32x32x16_bf16 v[96:111], v[220:223], v[120:123], v[96:111]
	v_mfma_f32_32x32x16_bf16 v[80:95], v[228:231], v[120:123], v[80:95]
	v_mfma_f32_32x32x16_bf16 v[96:111], v[224:227], v[124:127], v[96:111]
	v_mfma_f32_32x32x16_bf16 v[80:95], v[232:235], v[124:127], v[80:95]
	ds_read_b64_tr_b16 v[220:221], v187 offset:0x600
	ds_read_b64_tr_b16 v[222:223], v187 offset:0xe00
	ds_read_b64_tr_b16 v[224:225], v187 offset:0x1600
	ds_read_b64_tr_b16 v[226:227], v187 offset:0x1e00
	ds_read_b64_tr_b16 v[228:229], v187 offset:0x2600
	ds_read_b64_tr_b16 v[230:231], v187 offset:0x2e00
	ds_read_b64_tr_b16 v[232:233], v187 offset:0x3600
	ds_read_b64_tr_b16 v[234:235], v187 offset:0x3e00
	s_waitcnt lgkmcnt(15)
	v_mfma_f32_32x32x16_bf16 v[32:47], v[180:183], v[188:191], v[32:47]
	v_mfma_f32_32x32x16_bf16 v[32:47], v[176:179], v[192:195], v[32:47]
	v_mfma_f32_32x32x16_bf16 v[32:47], v[172:175], v[196:199], v[32:47]
	v_mfma_f32_32x32x16_bf16 v[32:47], v[168:171], v[236:239], v[32:47]
	s_waitcnt lgkmcnt(0)
	v_mfma_f32_32x32x16_bf16 v[0:15], v[180:183], v[220:223], v[0:15]
	v_mfma_f32_32x32x16_bf16 v[0:15], v[176:179], v[224:227], v[0:15]
	v_mfma_f32_32x32x16_bf16 v[0:15], v[172:175], v[228:231], v[0:15]
	v_mfma_f32_32x32x16_bf16 v[0:15], v[168:171], v[232:235], v[0:15]
	v_mfma_f32_32x32x16_bf16 v[16:31], v[180:183], v[164:167], v[16:31]
	v_mfma_f32_32x32x16_bf16 v[16:31], v[176:179], v[160:163], v[16:31]
	v_mfma_f32_32x32x16_bf16 v[16:31], v[172:175], v[156:159], v[16:31]
	v_mfma_f32_32x32x16_bf16 v[16:31], v[168:171], v[152:155], v[16:31]
	s_add_i32 s0, s51, 0x4000
	s_and_b32 s0, s0, 0xc000
	v_add_u32_e32 v240, s0, v217
	ds_read_b64_tr_b16 v[164:165], v240 offset:0
	ds_read_b64_tr_b16 v[166:167], v240 offset:0x800
	ds_read_b64_tr_b16 v[160:161], v240 offset:0x1000
	ds_read_b64_tr_b16 v[162:163], v240 offset:0x1800
	ds_read_b64_tr_b16 v[156:157], v240 offset:0x2000
	ds_read_b64_tr_b16 v[158:159], v240 offset:0x2800
	ds_read_b64_tr_b16 v[152:153], v240 offset:0x3000
	ds_read_b64_tr_b16 v[154:155], v240 offset:0x3800
	s_barrier
	v_max3_f32 v168, v96, v97, v98
	v_exp_f32_e32 v240, v96
	v_max3_f32 v169, v81, v82, v83
	v_exp_f32_e32 v241, v97
	v_max3_f32 v168, v168, v99, v100
	v_exp_f32_e32 v242, v98
	v_max3_f32 v169, v169, v84, v85
	v_exp_f32_e32 v243, v99
	v_max3_f32 v168, v168, v101, v102
	v_exp_f32_e32 v244, v100
	v_max3_f32 v169, v169, v86, v87
	v_exp_f32_e32 v245, v101
	v_max3_f32 v168, v168, v103, v104
	v_exp_f32_e32 v246, v102
	v_max3_f32 v169, v169, v88, v89
	v_exp_f32_e32 v247, v103
	v_max3_f32 v168, v168, v105, v106
	v_exp_f32_e32 v248, v104
	v_max3_f32 v169, v169, v90, v91
	v_exp_f32_e32 v249, v105
	v_max3_f32 v168, v168, v107, v108
	v_exp_f32_e32 v250, v106
	v_max3_f32 v169, v169, v92, v93
	v_exp_f32_e32 v251, v107
	v_max3_f32 v168, v168, v109, v110
	v_exp_f32_e32 v252, v108
	v_max3_f32 v169, v169, v94, v95
	v_exp_f32_e32 v253, v109
	v_max3_f32 v168, v168, v111, v80
	v_exp_f32_e32 v236, v110
	v_max_f32_e32 v168, v168, v169
	v_exp_f32_e32 v237, v111
	v_mov_b32_e32 v169, v168
	s_nop 1
	v_permlane32_swap_b32_e32 v168, v169
	v_max_f32_e32 v168, v168, v169
	v_cmp_ge_f32_e32 vcc, s83, v168
	v_mov_b32_e32 v187, 1.0
	s_cmp_eq_u64 vcc, exec
	s_cbranch_scc1 .Lsp_do0
	s_branch .LBB0_1171

; __device__ __forceinline__ float max3f(float a, float b, float c) { return __builtin_fmaxf(__builtin_fmaxf(a, b), c); }
; __device__ __forceinline__ void rowmax_adjust(f32x16& p0, f32x16& p1, float& m2, f32x16& negm, float& alpha, const bool first) {
;     constexpr float THR2 = THR * 1.4426950408889634f;
;     float pmax = max3f(p0[0], p0[1], p0[2]);
; #pragma unroll
;     for (int r = 3; r < 15; r += 2) pmax = max3f(pmax, p0[r], p0[r + 1]);
;     pmax = max3f(pmax, p0[15], p1[0]);
; #pragma unroll
;     for (int r = 1; r < 15; r += 2) pmax = max3f(pmax, p1[r], p1[r + 1]);
;     pmax = fmaxf(pmax, p1[15]);
;     { auto rr = __builtin_amdgcn_permlane32_swap(__float_as_uint(pmax), __float_as_uint(pmax), false, false);
;       pmax = fmaxf(__uint_as_float(rr[0]), __uint_as_float(rr[1])); }
;     if (!first && __builtin_expect(__all(pmax <= THR2), 1)) { alpha = 1.f; }
.Ld3_be_nopv:
	s_waitcnt lgkmcnt(0)
	s_and_b32 s0, s51, 0xc000
	v_add_u32_e32 v240, s0, v217
	ds_read_b64_tr_b16 v[164:165], v240 offset:0
	ds_read_b64_tr_b16 v[166:167], v240 offset:0x800
	ds_read_b64_tr_b16 v[160:161], v240 offset:0x1000
	ds_read_b64_tr_b16 v[162:163], v240 offset:0x1800
	ds_read_b64_tr_b16 v[156:157], v240 offset:0x2000
	ds_read_b64_tr_b16 v[158:159], v240 offset:0x2800
	ds_read_b64_tr_b16 v[152:153], v240 offset:0x3000
	ds_read_b64_tr_b16 v[154:155], v240 offset:0x3800
	s_mov_b64 s[0:1], s[60:61]
	s_barrier
	v_max3_f32 v168, v96, v97, v98
	v_exp_f32_e32 v240, v96
	v_max3_f32 v169, v81, v82, v83
	v_exp_f32_e32 v241, v97
	v_max3_f32 v168, v168, v99, v100
	v_exp_f32_e32 v242, v98
	v_max3_f32 v169, v169, v84, v85
	v_exp_f32_e32 v243, v99
	v_max3_f32 v168, v168, v101, v102
	v_exp_f32_e32 v244, v100
	v_max3_f32 v169, v169, v86, v87
	v_exp_f32_e32 v245, v101
	v_max3_f32 v168, v168, v103, v104
	v_exp_f32_e32 v246, v102
	v_max3_f32 v169, v169, v88, v89
	v_exp_f32_e32 v247, v103
	v_max3_f32 v168, v168, v105, v106
	v_exp_f32_e32 v248, v104
	v_max3_f32 v169, v169, v90, v91
	v_exp_f32_e32 v249, v105
	v_max3_f32 v168, v168, v107, v108
	v_exp_f32_e32 v250, v106
	v_max3_f32 v169, v169, v92, v93
	v_exp_f32_e32 v251, v107
	v_max3_f32 v168, v168, v109, v110
	v_exp_f32_e32 v252, v108
	v_max3_f32 v169, v169, v94, v95
	v_exp_f32_e32 v253, v109
	v_max3_f32 v168, v168, v111, v80
	v_exp_f32_e32 v236, v110
	v_max_f32_e32 v168, v168, v169
	v_exp_f32_e32 v237, v111
	v_mov_b32_e32 v169, v168
	s_nop 1
	v_permlane32_swap_b32_e32 v168, v169
	v_max_f32_e32 v168, v168, v169
	v_cmp_ge_f32_e32 vcc, s83, v168
	v_mov_b32_e32 v184, 1.0
	s_cmp_lg_u64 s[0:1], 0
	s_cbranch_scc1 .Lvt31_first
	s_cmp_lg_u64 vcc, exec
	s_cbranch_scc1 .Lvt31_rare
	s_branch .Lsp_de31

; __device__ __forceinline__ float max3f(float a, float b, float c) { return __builtin_fmaxf(__builtin_fmaxf(a, b), c); }
; __device__ __forceinline__ void rowmax_adjust(f32x16& p0, f32x16& p1, float& m2, f32x16& negm, float& alpha, const bool first) {
;     constexpr float THR2 = THR * 1.4426950408889634f;
;     float pmax = max3f(p0[0], p0[1], p0[2]);
; #pragma unroll
;     for (int r = 3; r < 15; r += 2) pmax = max3f(pmax, p0[r], p0[r + 1]);
;     pmax = max3f(pmax, p0[15], p1[0]);
; #pragma unroll
;     for (int r = 1; r < 15; r += 2) pmax = max3f(pmax, p1[r], p1[r + 1]);
;     pmax = fmaxf(pmax, p1[15]);
;     { auto rr = __builtin_amdgcn_permlane32_swap(__float_as_uint(pmax), __float_as_uint(pmax), false, false);
;       pmax = fmaxf(__uint_as_float(rr[0]), __uint_as_float(rr[1])); }
;     if (!first && __builtin_expect(__all(pmax <= THR2), 1)) { alpha = 1.f; }
.LBB0_1195:
	s_min_u32 s0, s64, 0x7f
	s_lshl_b32 s0, s0, 16
	s_add_i32 s16, s0, 0x40000
	s_add_u32 s0, s58, s16
	s_addc_u32 s1, s59, 0
	global_load_dwordx4 v[132:135], v200, s[0:1]
	global_load_dwordx4 v[128:131], v202, s[0:1]
	v_lshl_add_u64 v[80:81], v[204:205], 0, s[16:17]
	global_load_dwordx4 v[136:139], v[80:81], off
	s_waitcnt lgkmcnt(0)
	s_barrier
	s_or_b32 s0, s64, 1
	s_and_b32 s1, s0, 0xff
	s_mulk_i32 s1, 0xab
	s_bfe_u32 s1, s1, 0x70009
	s_mul_i32 s1, s1, 3
	s_sub_i32 s0, s0, s1
	s_and_b32 s0, s0, 0xff
	s_mulk_i32 s0, 0x2400
	v_add_u32_e32 v84, s0, v218
	s_and_b32 s0, s51, 0x8000
	v_add_u32_e32 v187, s0, v217
	ds_read_b128 v[80:83], v84
	ds_read_b128 v[192:195], v84 offset:4608
	ds_read_b128 v[188:191], v84 offset:32
	ds_read_b128 v[196:199], v84 offset:4640
	ds_read_b128 v[220:223], v84 offset:64
	ds_read_b128 v[228:231], v84 offset:4672
	ds_read_b128 v[224:227], v84 offset:96
	ds_read_b128 v[232:235], v84 offset:4704
	v_mfma_f32_32x32x16_bf16 v[48:63], v[180:183], v[164:167], v[48:63]
	v_mfma_f32_32x32x16_bf16 v[48:63], v[176:179], v[160:163], v[48:63]
	v_mfma_f32_32x32x16_bf16 v[48:63], v[172:175], v[156:159], v[48:63]
	v_mfma_f32_32x32x16_bf16 v[48:63], v[168:171], v[152:155], v[48:63]
	s_waitcnt lgkmcnt(7)
	v_mfma_f32_32x32x16_bf16 v[96:111], v[80:83], v[112:115], v[64:79]
	s_waitcnt lgkmcnt(6)
	v_mfma_f32_32x32x16_bf16 v[80:95], v[192:195], v[112:115], v[64:79]
	s_waitcnt lgkmcnt(5)
	v_mfma_f32_32x32x16_bf16 v[96:111], v[188:191], v[116:119], v[96:111]
	s_waitcnt lgkmcnt(4)
	v_mfma_f32_32x32x16_bf16 v[80:95], v[196:199], v[116:119], v[80:95]
	s_waitcnt lgkmcnt(0)
	ds_read_b64_tr_b16 v[188:189], v187 offset:0x200
	ds_read_b64_tr_b16 v[190:191], v187 offset:0xa00
	ds_read_b64_tr_b16 v[192:193], v187 offset:0x1200
	ds_read_b64_tr_b16 v[194:195], v187 offset:0x1a00
	ds_read_b64_tr_b16 v[196:197], v187 offset:0x2200
	ds_read_b64_tr_b16 v[198:199], v187 offset:0x2a00
	ds_read_b64_tr_b16 v[236:237], v187 offset:0x3200
	ds_read_b64_tr_b16 v[238:239], v187 offset:0x3a00
	ds_read_b64_tr_b16 v[164:165], v187 offset:0x400
	ds_read_b64_tr_b16 v[166:167], v187 offset:0xc00
	ds_read_b64_tr_b16 v[160:161], v187 offset:0x1400
	ds_read_b64_tr_b16 v[162:163], v187 offset:0x1c00
	ds_read_b64_tr_b16 v[156:157], v187 offset:0x2400
	ds_read_b64_tr_b16 v[158:159], v187 offset:0x2c00
	ds_read_b64_tr_b16 v[152:153], v187 offset:0x3400
	ds_read_b64_tr_b16 v[154:155], v187 offset:0x3c00
	v_mfma_f32_32x32x16_bf16 v[96:111], v[220:223], v[120:123], v[96:111]
	v_mfma_f32_32x32x16_bf16 v[80:95], v[228:231], v[120:123], v[80:95]
	v_mfma_f32_32x32x16_bf16 v[96:111], v[224:227], v[124:127], v[96:111]
	v_mfma_f32_32x32x16_bf16 v[80:95], v[232:235], v[124:127], v[80:95]
	ds_read_b64_tr_b16 v[220:221], v187 offset:0x600
	ds_read_b64_tr_b16 v[222:223], v187 offset:0xe00
	ds_read_b64_tr_b16 v[224:225], v187 offset:0x1600
	ds_read_b64_tr_b16 v[226:227], v187 offset:0x1e00
	ds_read_b64_tr_b16 v[228:229], v187 offset:0x2600
	ds_read_b64_tr_b16 v[230:231], v187 offset:0x2e00
	ds_read_b64_tr_b16 v[232:233], v187 offset:0x3600
	ds_read_b64_tr_b16 v[234:235], v187 offset:0x3e00
	s_waitcnt lgkmcnt(15)
	v_mfma_f32_32x32x16_bf16 v[32:47], v[180:183], v[188:191], v[32:47]
	v_mfma_f32_32x32x16_bf16 v[32:47], v[176:179], v[192:195], v[32:47]
	v_mfma_f32_32x32x16_bf16 v[32:47], v[172:175], v[196:199], v[32:47]
	v_mfma_f32_32x32x16_bf16 v[32:47], v[168:171], v[236:239], v[32:47]
	s_waitcnt lgkmcnt(0)
	v_mfma_f32_32x32x16_bf16 v[0:15], v[180:183], v[220:223], v[0:15]
	v_mfma_f32_32x32x16_bf16 v[0:15], v[176:179], v[224:227], v[0:15]
	v_mfma_f32_32x32x16_bf16 v[0:15], v[172:175], v[228:231], v[0:15]
	v_mfma_f32_32x32x16_bf16 v[0:15], v[168:171], v[232:235], v[0:15]
	v_mfma_f32_32x32x16_bf16 v[16:31], v[180:183], v[164:167], v[16:31]
	v_mfma_f32_32x32x16_bf16 v[16:31], v[176:179], v[160:163], v[16:31]
	v_mfma_f32_32x32x16_bf16 v[16:31], v[172:175], v[156:159], v[16:31]
	v_mfma_f32_32x32x16_bf16 v[16:31], v[168:171], v[152:155], v[16:31]
	s_add_i32 s0, s51, 0x4000
	s_and_b32 s0, s0, 0xc000
	v_add_u32_e32 v240, s0, v217
	ds_read_b64_tr_b16 v[164:165], v240 offset:0
	ds_read_b64_tr_b16 v[166:167], v240 offset:0x800
	ds_read_b64_tr_b16 v[160:161], v240 offset:0x1000
	ds_read_b64_tr_b16 v[162:163], v240 offset:0x1800
	ds_read_b64_tr_b16 v[156:157], v240 offset:0x2000
	ds_read_b64_tr_b16 v[158:159], v240 offset:0x2800
	ds_read_b64_tr_b16 v[152:153], v240 offset:0x3000
	ds_read_b64_tr_b16 v[154:155], v240 offset:0x3800
	s_barrier
	v_max3_f32 v168, v96, v97, v98
	v_exp_f32_e32 v240, v96
	v_max3_f32 v169, v81, v82, v83
	v_exp_f32_e32 v241, v97
	v_max3_f32 v168, v168, v99, v100
	v_exp_f32_e32 v242, v98
	v_max3_f32 v169, v169, v84, v85
	v_exp_f32_e32 v243, v99
	v_max3_f32 v168, v168, v101, v102
	v_exp_f32_e32 v244, v100
	v_max3_f32 v169, v169, v86, v87
	v_exp_f32_e32 v245, v101
	v_max3_f32 v168, v168, v103, v104
	v_exp_f32_e32 v246, v102
	v_max3_f32 v169, v169, v88, v89
	v_exp_f32_e32 v247, v103
	v_max3_f32 v168, v168, v105, v106
	v_exp_f32_e32 v248, v104
	v_max3_f32 v169, v169, v90, v91
	v_exp_f32_e32 v249, v105
	v_max3_f32 v168, v168, v107, v108
	v_exp_f32_e32 v250, v106
	v_max3_f32 v169, v169, v92, v93
	v_exp_f32_e32 v251, v107
	v_max3_f32 v168, v168, v109, v110
	v_exp_f32_e32 v252, v108
	v_max3_f32 v169, v169, v94, v95
	v_exp_f32_e32 v253, v109
	v_max3_f32 v168, v168, v111, v80
	v_exp_f32_e32 v236, v110
	v_max_f32_e32 v168, v168, v169
	v_exp_f32_e32 v237, v111
	v_mov_b32_e32 v169, v168
	s_nop 1
	v_permlane32_swap_b32_e32 v168, v169
	v_max_f32_e32 v168, v168, v169
	v_cmp_ge_f32_e32 vcc, s83, v168
	v_mov_b32_e32 v187, 1.0
	s_cmp_eq_u64 vcc, exec
	s_cbranch_scc1 .Lsp_do31
	s_branch .LBB0_1202
